# sel loop: wave-uniform sub flag formed on the scalar unit (no v_cndmask/v_readfirstlane round trip); fast path drops the add-zero steps (bit-identical sums)
# speedup vs baseline: 1.0071x; 1.0071x over previous
.LBB0_809:
	s_cmp_eq_u64 s[8:9], 0
	s_cselect_b64 s[14:15], -1, 0
	s_cmp_lg_u64 s[8:9], 0
	s_cselect_b64 s[16:17], -1, 0
	s_and_b64 vcc, exec, s[14:15]
	s_cbranch_vccnz .LBB0_811
	s_ff1_i32_b64 s3, s[8:9]
	s_lshl_b32 s3, s3, 6
	s_lshl_b32 s12, s2, 5
	s_or_b32 s3, s3, s12
	s_lshl_b32 s20, s3, 6
	s_cmp_eq_u32 s2, 0
	s_cselect_b64 s[12:13], -1, 0
	s_cmp_lt_i32 s3, s91
	s_cselect_b64 s[22:23], -1, 0
	s_and_b64 s[12:13], s[12:13], s[22:23]
	s_add_u32 s2, s8, -1
	s_addc_u32 s22, s9, -1
	s_nop 0
	s_and_b64 s[12:13], s[12:13], exec
	s_cselect_b32 s13, -1, s22
	s_cselect_b32 s12, -1, s2
	s_cselect_b32 s92, 1, 0
	s_and_b64 s[8:9], s[12:13], s[8:9]
	s_mov_b32 s2, s92
	s_mov_b32 s12, s20
	s_branch .LBB0_812

.Lsel_fast:
	s_waitcnt vmcnt(7)
	v_mfma_f32_32x32x16_bf16 v[80:95], v[128:131], v[96:99], 0
	s_lshr_b32 s13, s21, 6
	s_waitcnt vmcnt(6)
	v_mfma_f32_32x32x16_bf16 v[80:95], v[132:135], v[100:103], v[80:95]
	s_lshl_b64 s[16:17], 1, s13
	s_waitcnt vmcnt(5)
	v_mfma_f32_32x32x16_bf16 v[80:95], v[136:139], v[104:107], v[80:95]
	s_waitcnt vmcnt(4)
	v_mfma_f32_32x32x16_bf16 v[80:95], v[140:143], v[108:111], v[80:95]
	v_mfma_f32_32x32x16_bf16 v[64:79], v[128:131], v[112:115], 0
	v_and_b32_e32 v217, s17, v163
	v_and_b32_e32 v216, s16, v162
	v_cmp_ne_u64_e32 vcc, 0, v[216:217]
	s_nop 8
	v_exp_f32_e32 v80, v80
	v_exp_f32_e32 v81, v81
	v_exp_f32_e32 v82, v82
	v_exp_f32_e32 v83, v83
	v_mfma_f32_32x32x16_bf16 v[64:79], v[132:135], v[116:119], v[64:79]
	v_exp_f32_e32 v84, v84
	v_exp_f32_e32 v85, v85
	v_exp_f32_e32 v86, v86
	v_exp_f32_e32 v87, v87
	v_mfma_f32_32x32x16_bf16 v[64:79], v[136:139], v[120:123], v[64:79]
	v_pk_add_f32 v[218:219], v[80:81], v[82:83]
	v_cvt_pk_bf16_f32 v80, v80, v81
	v_cvt_pk_bf16_f32 v81, v82, v83
	v_cvt_pk_bf16_f32 v82, v84, v85
	v_cvt_pk_bf16_f32 v83, v86, v87
	v_pk_add_f32 v[218:219], v[84:85], v[218:219]
	v_pk_add_f32 v[218:219], v[86:87], v[218:219]
	v_mfma_f32_32x32x16_bf16 v[64:79], v[140:143], v[124:127], v[64:79]
	v_cndmask_b32_e32 v83, 0, v83, vcc
	v_cndmask_b32_e32 v82, 0, v82, vcc
	v_cndmask_b32_e32 v81, 0, v81, vcc
	v_cndmask_b32_e32 v80, 0, v80, vcc
	s_ashr_i32 s13, s12, 31
	v_lshl_add_u64 v[140:141], s[12:13], 1, v[210:211]
	global_load_dwordx4 v[128:131], v[140:141], off
	global_load_dwordx4 v[132:135], v[140:141], off offset:1024
	global_load_dwordx4 v[136:139], v[140:141], off offset:2048
	s_nop 0
	global_load_dwordx4 v[140:143], v[140:141], off offset:3072
	s_waitcnt vmcnt(7)
	v_mfma_f32_32x32x16_bf16 v[48:63], v[156:159], v[80:83], v[48:63]
	v_exp_f32_e32 v88, v88
	v_exp_f32_e32 v89, v89
	v_exp_f32_e32 v90, v90
	v_exp_f32_e32 v91, v91
	s_waitcnt vmcnt(6)
	v_mfma_f32_32x32x16_bf16 v[32:47], v[152:155], v[80:83], v[32:47]
	v_exp_f32_e32 v92, v92
	v_exp_f32_e32 v93, v93
	v_exp_f32_e32 v94, v94
	v_exp_f32_e32 v95, v95
	v_exp_f32_e32 v64, v64
	v_exp_f32_e32 v65, v65
	v_exp_f32_e32 v66, v66
	v_exp_f32_e32 v67, v67
	v_add_f32_e64 v218, v88, v218
	v_add_f32_e64 v219, v89, v219
	v_add_f32_e64 v218, v90, v218
	v_add_f32_e64 v219, v91, v219
	v_cvt_pk_bf16_f32 v84, v88, v89
	v_cvt_pk_bf16_f32 v85, v90, v91
	v_cvt_pk_bf16_f32 v86, v92, v93
	v_cvt_pk_bf16_f32 v87, v94, v95
	v_cndmask_b32_e32 v84, 0, v84, vcc
	v_cndmask_b32_e32 v85, 0, v85, vcc
	v_cndmask_b32_e32 v86, 0, v86, vcc
	v_cndmask_b32_e32 v87, 0, v87, vcc
	v_pk_add_f32 v[218:219], v[92:93], v[218:219]
	v_exp_f32_e32 v68, v68
	v_exp_f32_e32 v69, v69
	s_waitcnt vmcnt(5)
	v_mfma_f32_32x32x16_bf16 v[48:63], v[148:151], v[84:87], v[48:63]
	v_exp_f32_e32 v70, v70
	v_exp_f32_e32 v71, v71
	v_pk_add_f32 v[218:219], v[94:95], v[218:219]
	s_waitcnt vmcnt(4)
	v_mfma_f32_32x32x16_bf16 v[32:47], v[144:147], v[84:87], v[32:47]
	v_pk_add_f32 v[80:81], v[64:65], v[66:67]
	v_add_f32_e32 v218, v218, v219
	v_cvt_pk_bf16_f32 v64, v64, v65
	v_cvt_pk_bf16_f32 v65, v66, v67
	v_cvt_pk_bf16_f32 v66, v68, v69
	v_cvt_pk_bf16_f32 v67, v70, v71
	v_pk_add_f32 v[80:81], v[68:69], v[80:81]
	v_cndmask_b32_e32 v216, 0, v218, vcc
	v_cndmask_b32_e32 v64, 0, v64, vcc
	v_cndmask_b32_e32 v65, 0, v65, vcc
	v_cndmask_b32_e32 v66, 0, v66, vcc
	v_cndmask_b32_e32 v67, 0, v67, vcc
	v_add_f32_e32 v215, v215, v216
	v_add_f32_e64 v68, v70, v80
	v_add_f32_e64 v69, v71, v81
	v_mfma_f32_32x32x16_bf16 v[16:31], v[156:159], v[64:67], v[16:31]
	v_exp_f32_e32 v72, v72
	v_exp_f32_e32 v73, v73
	v_exp_f32_e32 v74, v74
	v_exp_f32_e32 v75, v75
	v_mfma_f32_32x32x16_bf16 v[0:15], v[152:155], v[64:67], v[0:15]
	v_exp_f32_e32 v76, v76
	v_exp_f32_e32 v77, v77
	v_exp_f32_e32 v70, v78
	v_exp_f32_e32 v71, v79
	v_pk_add_f32 v[68:69], v[72:73], v[68:69]
	v_add_f32_e64 v68, v74, v68
	v_add_f32_e64 v69, v75, v69
	v_pk_add_f32 v[68:69], v[76:77], v[68:69]
	v_cvt_pk_bf16_f32 v72, v72, v73
	v_cvt_pk_bf16_f32 v65, v74, v75
	v_cvt_pk_bf16_f32 v66, v76, v77
	v_cvt_pk_bf16_f32 v67, v70, v71
	v_pk_add_f32 v[68:69], v[70:71], v[68:69]
	v_cndmask_b32_e32 v64, 0, v72, vcc
	v_cndmask_b32_e32 v65, 0, v65, vcc
	v_cndmask_b32_e32 v66, 0, v66, vcc
	v_cndmask_b32_e32 v67, 0, v67, vcc
	v_add_f32_e32 v68, v68, v69
	s_nop 0
	v_mfma_f32_32x32x16_bf16 v[16:31], v[148:151], v[64:67], v[16:31]
	v_cndmask_b32_e32 v68, 0, v68, vcc
	v_mfma_f32_32x32x16_bf16 v[0:15], v[144:147], v[64:67], v[0:15]
	v_add_f32_e32 v214, v214, v68
	s_mov_b32 s62, s20
	s_mov_b32 s21, s3
	s_branch .LBB0_809
